# attention loops: trip bounds and fifth-piece LDS targets kept in SGPRs, base advance folded into the burst as m0 wait-state filler, exit test on the tile counter, wave-dependent wait without a taken b
# speedup vs baseline: 1.0217x; 1.0017x over previous
.Ldk_p3:
	s_add_i32 m0, s28, s32
	s_nop 0
	global_load_lds_dwordx4 v130, s[80:81]
	s_add_i32 m0, m0, 0x2000
	s_nop 0
	global_load_lds_dwordx4 v131, s[80:81]
	s_cmp_eq_u32 s56, 0
	s_cbranch_scc1 .Ldv_p3
	s_cmp_gt_u32 s56, 4
	s_cbranch_scc1 .Ldv_p3
	s_add_i32 m0, s28, s32
	s_add_i32 m0, m0, 0x3c00
	s_nop 0
	global_load_lds_dwordx4 v132, s[80:81]
.Ldv_p3:
	s_branch .LBB0_228

.LBB0_228:
	s_and_b64 vcc, exec, s[16:17]
	s_cbranch_vccnz .LA_entry
	s_add_i32 s86, s9, 1
	s_add_i32 s87, s66, -1
	s_sub_u32 s80, s80, 0x20000
	s_subb_u32 s81, s81, 0
	s_add_i32 s5, s32, 0x16400
	s_add_i32 s28, s32, 0xc400
	s_add_i32 s29, s32, 0x11400
	s_cmp_eq_u32 s56, 0
	s_cselect_b32 s5, 0x4000, s5
	s_cselect_b32 s28, 0x8400, s28
	s_cselect_b32 s29, 0x24400, s29
.LB1_top:
	s_cmp_ge_u32 s65, s87
	s_cbranch_scc1 .Ltl_b1
	s_mov_b32 m0, s32
	s_add_u32 s80, s80, 0x20000
	s_addc_u32 s81, s81, 0
	global_load_lds_dwordx4 v128, s[80:81]
	s_add_i32 m0, m0, 0x2000
	s_nop 0
	global_load_lds_dwordx4 v129, s[80:81]
	s_add_i32 m0, s32, 0x12800
	s_nop 0
	global_load_lds_dwordx4 v130, s[80:81]
	s_add_i32 m0, m0, 0x2000
	s_nop 0
	global_load_lds_dwordx4 v131, s[80:81]
	s_mov_b32 m0, s5
	s_cmp_gt_i32 s65, s86
	global_load_lds_dwordx4 v132, s[80:81]
.Lnod_b1:
	s_cbranch_scc1 .LB1_skip
	v_max_f32_e32 v176, v96, v80
	v_max3_f32 v177, v81, v98, v82
	v_max3_f32 v176, v176, v97, v99
	v_max3_f32 v177, v177, v100, v84
	v_max3_f32 v176, v176, v83, v101
	v_max3_f32 v177, v177, v102, v86
	v_max3_f32 v176, v176, v85, v103
	v_max3_f32 v177, v177, v104, v88
	v_max3_f32 v176, v176, v87, v105
	v_max3_f32 v177, v177, v106, v90
	v_max3_f32 v176, v176, v89, v107
	v_max3_f32 v177, v177, v108, v92
	v_max3_f32 v176, v176, v91, v109
	v_max3_f32 v177, v177, v110, v94
	v_max3_f32 v176, v176, v93, v111
	v_max3_f32 v176, v176, v95, v177
	v_mov_b32_e32 v177, v176
	s_nop 1
	v_permlane32_swap_b32_e32 v176, v177
	v_max_f32_e32 v176, v176, v177
	v_cmp_lt_f32_e32 vcc, 0x41000000, v176
	s_cbranch_vccnz .Lrs_b1
.Latt_b1_exp:
	v_exp_f32_e32 v96, v96
	v_exp_f32_e32 v97, v97
	v_exp_f32_e32 v176, v80
	v_exp_f32_e32 v177, v81
	v_exp_f32_e32 v98, v98
	v_exp_f32_e32 v99, v99
	v_exp_f32_e32 v178, v82
	v_exp_f32_e32 v179, v83
	v_exp_f32_e32 v100, v100
	v_exp_f32_e32 v101, v101
	v_exp_f32_e32 v180, v84
	v_exp_f32_e32 v181, v85
	v_exp_f32_e32 v102, v102
	v_exp_f32_e32 v103, v103
	v_exp_f32_e32 v182, v86
	v_exp_f32_e32 v183, v87
	v_exp_f32_e32 v104, v104
	v_exp_f32_e32 v105, v105
	v_exp_f32_e32 v184, v88
	v_exp_f32_e32 v185, v89
	v_exp_f32_e32 v106, v106
	v_exp_f32_e32 v107, v107
	v_exp_f32_e32 v186, v90
	v_exp_f32_e32 v187, v91
	v_exp_f32_e32 v108, v108
	v_exp_f32_e32 v109, v109
	v_exp_f32_e32 v188, v92
	v_exp_f32_e32 v189, v93
	v_exp_f32_e32 v110, v110
	v_exp_f32_e32 v111, v111
	v_exp_f32_e32 v190, v94
	v_exp_f32_e32 v191, v95
	v_cvt_pk_bf16_f32 v80, v96, v97
	v_cvt_pk_bf16_f32 v81, v98, v99
	v_cvt_pk_bf16_f32 v82, v100, v101
	v_cvt_pk_bf16_f32 v83, v102, v103
	v_cvt_pk_bf16_f32 v84, v104, v105
	v_cvt_pk_bf16_f32 v85, v106, v107
	v_cvt_pk_bf16_f32 v86, v108, v109
	v_cvt_pk_bf16_f32 v87, v110, v111
	v_cvt_pk_bf16_f32 v88, v176, v177
	v_cvt_pk_bf16_f32 v89, v178, v179
	v_cvt_pk_bf16_f32 v90, v180, v181
	v_cvt_pk_bf16_f32 v91, v182, v183
	v_cvt_pk_bf16_f32 v92, v184, v185
	v_cvt_pk_bf16_f32 v93, v186, v187
	v_cvt_pk_bf16_f32 v94, v188, v189
	v_cvt_pk_bf16_f32 v95, v190, v191
	v_pk_add_f32 v[96:97], v[96:97], v[100:101]
	v_pk_add_f32 v[98:99], v[98:99], v[102:103]
	v_pk_add_f32 v[176:177], v[176:177], v[180:181]
	v_pk_add_f32 v[178:179], v[178:179], v[182:183]
	v_pk_add_f32 v[96:97], v[96:97], v[104:105]
	v_pk_add_f32 v[98:99], v[98:99], v[106:107]
	v_pk_add_f32 v[176:177], v[176:177], v[184:185]
	v_pk_add_f32 v[178:179], v[178:179], v[186:187]
	v_pk_add_f32 v[96:97], v[96:97], v[108:109]
	v_pk_add_f32 v[98:99], v[98:99], v[110:111]
	v_pk_add_f32 v[176:177], v[176:177], v[188:189]
	v_pk_add_f32 v[178:179], v[178:179], v[190:191]
	v_pk_add_f32 v[96:97], v[96:97], v[98:99]
	v_pk_add_f32 v[176:177], v[176:177], v[178:179]
	s_nop 0
	v_pk_add_f32 v[96:97], v[96:97], v[176:177]
	s_nop 0
	v_add_f32_e32 v96, v96, v97
	v_add_f32_e32 v172, v172, v96
	s_cmp_ge_i32 s65, s86
	s_cbranch_scc1 .LB1_pvonly
	v_add_u32_e32 v205, 0x5000, v165
	v_add_u32_e32 v206, 0x20400, v192
	s_cmp_lt_u32 s65, s87
	s_cbranch_scc0 .Lw0_b1
	s_waitcnt vmcnt(5) lgkmcnt(0)

.LB1_end:
	s_add_i32 s65, s65, 1
	s_add_i32 s33, s33, -1
	s_cmp_gt_u32 s65, s66
	s_cbranch_scc1 .LB1_exit
.LB2_top:
	s_cmp_ge_u32 s65, s87
	s_cbranch_scc1 .Ltl_b2
	s_add_i32 m0, s32, 0x4400
	s_add_u32 s80, s80, 0x20000
	s_addc_u32 s81, s81, 0
	global_load_lds_dwordx4 v128, s[80:81]
	s_add_i32 m0, m0, 0x2000
	s_nop 0
	global_load_lds_dwordx4 v129, s[80:81]
	s_add_i32 m0, s32, 0x8800
	s_nop 0
	global_load_lds_dwordx4 v130, s[80:81]
	s_add_i32 m0, m0, 0x2000
	s_nop 0
	global_load_lds_dwordx4 v131, s[80:81]
	s_mov_b32 m0, s28
	s_cmp_gt_i32 s65, s86
	global_load_lds_dwordx4 v132, s[80:81]

.Latt_b2_exp:
	v_exp_f32_e32 v96, v96
	v_exp_f32_e32 v97, v97
	v_exp_f32_e32 v176, v80
	v_exp_f32_e32 v177, v81
	v_exp_f32_e32 v98, v98
	v_exp_f32_e32 v99, v99
	v_exp_f32_e32 v178, v82
	v_exp_f32_e32 v179, v83
	v_exp_f32_e32 v100, v100
	v_exp_f32_e32 v101, v101
	v_exp_f32_e32 v180, v84
	v_exp_f32_e32 v181, v85
	v_exp_f32_e32 v102, v102
	v_exp_f32_e32 v103, v103
	v_exp_f32_e32 v182, v86
	v_exp_f32_e32 v183, v87
	v_exp_f32_e32 v104, v104
	v_exp_f32_e32 v105, v105
	v_exp_f32_e32 v184, v88
	v_exp_f32_e32 v185, v89
	v_exp_f32_e32 v106, v106
	v_exp_f32_e32 v107, v107
	v_exp_f32_e32 v186, v90
	v_exp_f32_e32 v187, v91
	v_exp_f32_e32 v108, v108
	v_exp_f32_e32 v109, v109
	v_exp_f32_e32 v188, v92
	v_exp_f32_e32 v189, v93
	v_exp_f32_e32 v110, v110
	v_exp_f32_e32 v111, v111
	v_exp_f32_e32 v190, v94
	v_exp_f32_e32 v191, v95
	v_cvt_pk_bf16_f32 v80, v96, v97
	v_cvt_pk_bf16_f32 v81, v98, v99
	v_cvt_pk_bf16_f32 v82, v100, v101
	v_cvt_pk_bf16_f32 v83, v102, v103
	v_cvt_pk_bf16_f32 v84, v104, v105
	v_cvt_pk_bf16_f32 v85, v106, v107
	v_cvt_pk_bf16_f32 v86, v108, v109
	v_cvt_pk_bf16_f32 v87, v110, v111
	v_cvt_pk_bf16_f32 v88, v176, v177
	v_cvt_pk_bf16_f32 v89, v178, v179
	v_cvt_pk_bf16_f32 v90, v180, v181
	v_cvt_pk_bf16_f32 v91, v182, v183
	v_cvt_pk_bf16_f32 v92, v184, v185
	v_cvt_pk_bf16_f32 v93, v186, v187
	v_cvt_pk_bf16_f32 v94, v188, v189
	v_cvt_pk_bf16_f32 v95, v190, v191
	v_pk_add_f32 v[96:97], v[96:97], v[100:101]
	v_pk_add_f32 v[98:99], v[98:99], v[102:103]
	v_pk_add_f32 v[176:177], v[176:177], v[180:181]
	v_pk_add_f32 v[178:179], v[178:179], v[182:183]
	v_pk_add_f32 v[96:97], v[96:97], v[104:105]
	v_pk_add_f32 v[98:99], v[98:99], v[106:107]
	v_pk_add_f32 v[176:177], v[176:177], v[184:185]
	v_pk_add_f32 v[178:179], v[178:179], v[186:187]
	v_pk_add_f32 v[96:97], v[96:97], v[108:109]
	v_pk_add_f32 v[98:99], v[98:99], v[110:111]
	v_pk_add_f32 v[176:177], v[176:177], v[188:189]
	v_pk_add_f32 v[178:179], v[178:179], v[190:191]
	v_pk_add_f32 v[96:97], v[96:97], v[98:99]
	v_pk_add_f32 v[176:177], v[176:177], v[178:179]
	s_nop 0
	v_pk_add_f32 v[96:97], v[96:97], v[176:177]
	s_nop 0
	v_add_f32_e32 v96, v96, v97
	v_add_f32_e32 v172, v172, v96
	s_cmp_ge_i32 s65, s86
	s_cbranch_scc1 .LB2_pvonly
	v_add_u32_e32 v205, 0xa000, v165
	v_add_u32_e32 v206, 0x0, v192
	s_cmp_lt_u32 s65, s87
	s_cbranch_scc0 .Lw0_b2
	s_waitcnt vmcnt(5) lgkmcnt(0)

.LB0_top:
	s_cmp_ge_u32 s65, s87
	s_cbranch_scc1 .Ltl_b0
	s_add_i32 m0, s32, 0x20400
	s_add_u32 s80, s80, 0x20000
	s_addc_u32 s81, s81, 0
	global_load_lds_dwordx4 v128, s[80:81]
	s_add_i32 m0, m0, 0x2000
	s_nop 0
	global_load_lds_dwordx4 v129, s[80:81]
	s_add_i32 m0, s32, 0xd800
	s_nop 0
	global_load_lds_dwordx4 v130, s[80:81]
	s_add_i32 m0, m0, 0x2000
	s_nop 0
	global_load_lds_dwordx4 v131, s[80:81]
	s_mov_b32 m0, s29
	s_cmp_gt_i32 s65, s86
	global_load_lds_dwordx4 v132, s[80:81]

.Latt_b0_exp:
	v_exp_f32_e32 v96, v96
	v_exp_f32_e32 v97, v97
	v_exp_f32_e32 v176, v80
	v_exp_f32_e32 v177, v81
	v_exp_f32_e32 v98, v98
	v_exp_f32_e32 v99, v99
	v_exp_f32_e32 v178, v82
	v_exp_f32_e32 v179, v83
	v_exp_f32_e32 v100, v100
	v_exp_f32_e32 v101, v101
	v_exp_f32_e32 v180, v84
	v_exp_f32_e32 v181, v85
	v_exp_f32_e32 v102, v102
	v_exp_f32_e32 v103, v103
	v_exp_f32_e32 v182, v86
	v_exp_f32_e32 v183, v87
	v_exp_f32_e32 v104, v104
	v_exp_f32_e32 v105, v105
	v_exp_f32_e32 v184, v88
	v_exp_f32_e32 v185, v89
	v_exp_f32_e32 v106, v106
	v_exp_f32_e32 v107, v107
	v_exp_f32_e32 v186, v90
	v_exp_f32_e32 v187, v91
	v_exp_f32_e32 v108, v108
	v_exp_f32_e32 v109, v109
	v_exp_f32_e32 v188, v92
	v_exp_f32_e32 v189, v93
	v_exp_f32_e32 v110, v110
	v_exp_f32_e32 v111, v111
	v_exp_f32_e32 v190, v94
	v_exp_f32_e32 v191, v95
	v_cvt_pk_bf16_f32 v80, v96, v97
	v_cvt_pk_bf16_f32 v81, v98, v99
	v_cvt_pk_bf16_f32 v82, v100, v101
	v_cvt_pk_bf16_f32 v83, v102, v103
	v_cvt_pk_bf16_f32 v84, v104, v105
	v_cvt_pk_bf16_f32 v85, v106, v107
	v_cvt_pk_bf16_f32 v86, v108, v109
	v_cvt_pk_bf16_f32 v87, v110, v111
	v_cvt_pk_bf16_f32 v88, v176, v177
	v_cvt_pk_bf16_f32 v89, v178, v179
	v_cvt_pk_bf16_f32 v90, v180, v181
	v_cvt_pk_bf16_f32 v91, v182, v183
	v_cvt_pk_bf16_f32 v92, v184, v185
	v_cvt_pk_bf16_f32 v93, v186, v187
	v_cvt_pk_bf16_f32 v94, v188, v189
	v_cvt_pk_bf16_f32 v95, v190, v191
	v_pk_add_f32 v[96:97], v[96:97], v[100:101]
	v_pk_add_f32 v[98:99], v[98:99], v[102:103]
	v_pk_add_f32 v[176:177], v[176:177], v[180:181]
	v_pk_add_f32 v[178:179], v[178:179], v[182:183]
	v_pk_add_f32 v[96:97], v[96:97], v[104:105]
	v_pk_add_f32 v[98:99], v[98:99], v[106:107]
	v_pk_add_f32 v[176:177], v[176:177], v[184:185]
	v_pk_add_f32 v[178:179], v[178:179], v[186:187]
	v_pk_add_f32 v[96:97], v[96:97], v[108:109]
	v_pk_add_f32 v[98:99], v[98:99], v[110:111]
	v_pk_add_f32 v[176:177], v[176:177], v[188:189]
	v_pk_add_f32 v[178:179], v[178:179], v[190:191]
	v_pk_add_f32 v[96:97], v[96:97], v[98:99]
	v_pk_add_f32 v[176:177], v[176:177], v[178:179]
	s_nop 0
	v_pk_add_f32 v[96:97], v[96:97], v[176:177]
	s_nop 0
	v_add_f32_e32 v96, v96, v97
	v_add_f32_e32 v172, v172, v96
	s_cmp_ge_i32 s65, s86
	s_cbranch_scc1 .LB0_pvonly
	v_add_u32_e32 v205, 0x0, v165
	v_add_u32_e32 v206, 0x4400, v192
	s_cmp_lt_u32 s65, s87
	s_cbranch_scc0 .Lw0_b0
	s_waitcnt vmcnt(5) lgkmcnt(0)

.LB0_end:
	s_add_i32 s65, s65, 1
	s_add_i32 s33, s33, -1
	s_cmp_gt_u32 s65, s66
	s_cbranch_scc1 .LB0_exit
	s_branch .LB1_top
.LA_entry:
	s_add_i32 s87, s66, -2
	s_add_i32 s5, s32, 0xc400
	s_add_i32 s28, s32, 0x11400
	s_add_i32 s29, s32, 0x16400

.Latt_a1_stg:
	s_cmp_le_u32 s65, s87
	s_cbranch_scc0 .Lw0_a1
	s_cmp_eq_u32 s56, 4
	s_cbranch_scc1 .Lw5_a1
	s_waitcnt vmcnt(4) lgkmcnt(0)

.Lwd_a1:
	s_barrier
	s_cmp_ge_u32 s65, s87
	s_cbranch_scc1 .Ltl_a1
	s_add_i32 m0, s32, 0x4400
	s_add_u32 s80, s80, 0x20000
	s_addc_u32 s81, s81, 0
	global_load_lds_dwordx4 v128, s[80:81]
	s_add_i32 m0, m0, 0x2000
	s_nop 0
	global_load_lds_dwordx4 v129, s[80:81]
	s_add_i32 m0, s32, 0x8800
	s_nop 0
	global_load_lds_dwordx4 v130, s[80:81]
	s_add_i32 m0, m0, 0x2000
	s_cmp_eq_u32 s56, 4
	global_load_lds_dwordx4 v131, s[80:81]
	s_cbranch_scc0 .Lnod_a1
	s_mov_b32 m0, s5
	s_nop 0
	global_load_lds_dwordx4 v132, s[80:81]

.Lwd_a2:
	s_barrier
	s_cmp_ge_u32 s65, s87
	s_cbranch_scc1 .Ltl_a2
	s_add_i32 m0, s32, 0x20400
	s_add_u32 s80, s80, 0x20000
	s_addc_u32 s81, s81, 0
	global_load_lds_dwordx4 v128, s[80:81]
	s_add_i32 m0, m0, 0x2000
	s_nop 0
	global_load_lds_dwordx4 v129, s[80:81]
	s_add_i32 m0, s32, 0xd800
	s_nop 0
	global_load_lds_dwordx4 v130, s[80:81]
	s_add_i32 m0, m0, 0x2000
	s_cmp_eq_u32 s56, 4
	global_load_lds_dwordx4 v131, s[80:81]
	s_cbranch_scc0 .Lnod_a2
	s_mov_b32 m0, s28
	s_nop 0
	global_load_lds_dwordx4 v132, s[80:81]

.Lwd_a0:
	s_barrier
	s_cmp_ge_u32 s65, s87
	s_cbranch_scc1 .Ltl_a0
	s_mov_b32 m0, s32
	s_add_u32 s80, s80, 0x20000
	s_addc_u32 s81, s81, 0
	global_load_lds_dwordx4 v128, s[80:81]
	s_add_i32 m0, m0, 0x2000
	s_nop 0
	global_load_lds_dwordx4 v129, s[80:81]
	s_add_i32 m0, s32, 0x12800
	s_nop 0
	global_load_lds_dwordx4 v130, s[80:81]
	s_add_i32 m0, m0, 0x2000
	s_cmp_eq_u32 s56, 4
	global_load_lds_dwordx4 v131, s[80:81]
	s_cbranch_scc0 .Lnod_a0
	s_mov_b32 m0, s29
	s_nop 0
	global_load_lds_dwordx4 v132, s[80:81]

.Ltl_b1:
	s_cmp_ge_u32 s65, s66
	s_cbranch_scc1 .Ltl2_b1
	s_add_u32 s80, s80, 0x20000
	s_addc_u32 s81, s81, 0
	s_add_i32 m0, s32, 0x12800
	s_nop 0
	global_load_lds_dwordx4 v130, s[80:81]
	s_add_i32 m0, m0, 0x2000
	s_cmp_eq_u32 s56, 0
	global_load_lds_dwordx4 v131, s[80:81]
	s_cbranch_scc1 .Ltl2_b1
	s_mov_b32 m0, s5
	s_nop 0
	global_load_lds_dwordx4 v132, s[80:81]
.Ltl2_b1:
	s_cmp_gt_i32 s65, s86
	s_branch .Lnod_b1

.LB1_skip:
	s_cmp_lt_u32 s65, s87
	s_cbranch_scc0 .Lw0_b1s
	s_waitcnt vmcnt(5) lgkmcnt(0)

.Lbn_b1:
	s_lshl_b32 s68, s65, 8
	s_addk_i32 s68, 0xfd00
	s_waitcnt lgkmcnt(0)
	s_add_i32 s4, s68, 0x100
	v_add_u32_e32 v205, s4, v204
	v_add_u32_e32 v176, 0x17d00, v205
	v_add_u32_e32 v178, 0x17d80, v205
	ds_read2_b32 v[176:177], v176 offset1:1
	ds_read2_b32 v[178:179], v178 offset1:1
	v_add_u32_e32 v180, 0x17d08, v205
	v_add_u32_e32 v182, 0x17d88, v205
	v_add_u32_e32 v184, 0x17d20, v205
	v_add_u32_e32 v186, 0x17da0, v205
	v_add_u32_e32 v188, 0x17d28, v205
	v_add_u32_e32 v190, 0x17da8, v205
	v_add_u32_e32 v206, 0x17d40, v205
	v_add_u32_e32 v210, 0x17dc0, v205
	v_add_u32_e32 v212, 0x17d48, v205
	v_add_u32_e32 v221, 0x17dc8, v205
	ds_read2_b32 v[180:181], v180 offset1:1
	ds_read2_b32 v[182:183], v182 offset1:1
	ds_read2_b32 v[184:185], v184 offset1:1
	ds_read2_b32 v[186:187], v186 offset1:1
	ds_read2_b32 v[188:189], v188 offset1:1
	ds_read2_b32 v[190:191], v190 offset1:1
	ds_read2_b32 v[206:207], v206 offset1:1
	ds_read2_b32 v[210:211], v210 offset1:1
	ds_read2_b32 v[212:213], v212 offset1:1
	ds_read2_b32 v[224:225], v221 offset1:1
	v_add_u32_e32 v221, 0x17d60, v205
	v_add_u32_e32 v223, 0x17de0, v205
	ds_read2_b32 v[226:227], v221 offset1:1
	ds_read2_b32 v[228:229], v223 offset1:1
	v_add_u32_e32 v221, 0x17d68, v205
	v_add_u32_e32 v205, 0x17de8, v205
	ds_read2_b32 v[230:231], v221 offset1:1
	s_waitcnt lgkmcnt(14)
	v_pk_add_f32 v[96:97], v[96:97], v[176:177]
	ds_read2_b32 v[176:177], v205 offset1:1
	s_waitcnt lgkmcnt(3)
	v_pk_add_f32 v[108:109], v[108:109], v[226:227]
	v_pk_add_f32 v[106:107], v[106:107], v[212:213]
	s_waitcnt lgkmcnt(1)
	v_pk_add_f32 v[110:111], v[110:111], v[230:231]
	v_pk_add_f32 v[104:105], v[104:105], v[206:207]
	v_pk_add_f32 v[102:103], v[102:103], v[188:189]
	v_pk_add_f32 v[100:101], v[100:101], v[184:185]
	v_pk_add_f32 v[98:99], v[98:99], v[180:181]
	s_waitcnt lgkmcnt(0)
	v_pk_add_f32 v[94:95], v[94:95], v[176:177]
	v_pk_add_f32 v[92:93], v[92:93], v[228:229]
	v_pk_add_f32 v[90:91], v[90:91], v[224:225]
	v_pk_add_f32 v[88:89], v[88:89], v[210:211]
	v_pk_add_f32 v[86:87], v[86:87], v[190:191]
	v_pk_add_f32 v[84:85], v[84:85], v[186:187]
	v_pk_add_f32 v[82:83], v[82:83], v[182:183]
	v_pk_add_f32 v[80:81], v[80:81], v[178:179]
	s_nop 0
	s_branch .LB1_end

.Ltl_b2:
	s_cmp_ge_u32 s65, s66
	s_cbranch_scc1 .Ltl2_b2
	s_add_u32 s80, s80, 0x20000
	s_addc_u32 s81, s81, 0
	s_add_i32 m0, s32, 0x8800
	s_nop 0
	global_load_lds_dwordx4 v130, s[80:81]
	s_add_i32 m0, m0, 0x2000
	s_cmp_eq_u32 s56, 0
	global_load_lds_dwordx4 v131, s[80:81]
	s_cbranch_scc1 .Ltl2_b2
	s_mov_b32 m0, s28
	s_nop 0
	global_load_lds_dwordx4 v132, s[80:81]

.Ltl_b0:
	s_cmp_ge_u32 s65, s66
	s_cbranch_scc1 .Ltl2_b0
	s_add_u32 s80, s80, 0x20000
	s_addc_u32 s81, s81, 0
	s_add_i32 m0, s32, 0xd800
	s_nop 0
	global_load_lds_dwordx4 v130, s[80:81]
	s_add_i32 m0, m0, 0x2000
	s_cmp_eq_u32 s56, 0
	global_load_lds_dwordx4 v131, s[80:81]
	s_cbranch_scc1 .Ltl2_b0
	s_mov_b32 m0, s29
	s_nop 0
	global_load_lds_dwordx4 v132, s[80:81]

.Lba_a1:
	s_lshl_b32 s68, s65, 8
	s_addk_i32 s68, 0xfd00
	s_waitcnt lgkmcnt(0)
	v_add_u32_e32 v205, s68, v204
	v_add_u32_e32 v176, 0x17d00, v205
	v_add_u32_e32 v178, 0x17d80, v205
	ds_read2_b32 v[176:177], v176 offset1:1
	ds_read2_b32 v[178:179], v178 offset1:1
	v_add_u32_e32 v180, 0x17d08, v205
	v_add_u32_e32 v182, 0x17d88, v205
	v_add_u32_e32 v184, 0x17d20, v205
	v_add_u32_e32 v186, 0x17da0, v205
	v_add_u32_e32 v188, 0x17d28, v205
	v_add_u32_e32 v190, 0x17da8, v205
	v_add_u32_e32 v206, 0x17d40, v205
	v_add_u32_e32 v210, 0x17dc0, v205
	v_add_u32_e32 v212, 0x17d48, v205
	v_add_u32_e32 v221, 0x17dc8, v205
	ds_read2_b32 v[180:181], v180 offset1:1
	ds_read2_b32 v[182:183], v182 offset1:1
	ds_read2_b32 v[184:185], v184 offset1:1
	ds_read2_b32 v[186:187], v186 offset1:1
	ds_read2_b32 v[188:189], v188 offset1:1
	ds_read2_b32 v[190:191], v190 offset1:1
	ds_read2_b32 v[206:207], v206 offset1:1
	ds_read2_b32 v[210:211], v210 offset1:1
	ds_read2_b32 v[212:213], v212 offset1:1
	ds_read2_b32 v[224:225], v221 offset1:1
	v_add_u32_e32 v221, 0x17d60, v205
	v_add_u32_e32 v223, 0x17de0, v205
	ds_read2_b32 v[226:227], v221 offset1:1
	ds_read2_b32 v[228:229], v223 offset1:1
	v_add_u32_e32 v221, 0x17d68, v205
	v_add_u32_e32 v205, 0x17de8, v205
	ds_read2_b32 v[230:231], v221 offset1:1
	s_waitcnt lgkmcnt(14)
	v_pk_add_f32 v[96:97], v[96:97], v[176:177]
	ds_read2_b32 v[176:177], v205 offset1:1
	s_waitcnt lgkmcnt(3)
	v_pk_add_f32 v[108:109], v[108:109], v[226:227]
	v_pk_add_f32 v[106:107], v[106:107], v[212:213]
	s_waitcnt lgkmcnt(1)
	v_pk_add_f32 v[110:111], v[110:111], v[230:231]
	v_pk_add_f32 v[104:105], v[104:105], v[206:207]
	v_pk_add_f32 v[102:103], v[102:103], v[188:189]
	v_pk_add_f32 v[100:101], v[100:101], v[184:185]
	v_pk_add_f32 v[98:99], v[98:99], v[180:181]
	s_waitcnt lgkmcnt(0)
	v_pk_add_f32 v[94:95], v[94:95], v[176:177]
	v_pk_add_f32 v[92:93], v[92:93], v[228:229]
	v_pk_add_f32 v[90:91], v[90:91], v[224:225]
	v_pk_add_f32 v[88:89], v[88:89], v[210:211]
	v_pk_add_f32 v[86:87], v[86:87], v[190:191]
	v_pk_add_f32 v[84:85], v[84:85], v[186:187]
	v_pk_add_f32 v[82:83], v[82:83], v[182:183]
	v_pk_add_f32 v[80:81], v[80:81], v[178:179]
	s_nop 0
	s_branch .Latt_a1_stg

.Ltl_a1:
	s_add_i32 s4, s65, 1
	s_cmp_ge_u32 s4, s66
	s_cbranch_scc1 .Ltl2_a1
	s_add_u32 s80, s80, 0x20000
	s_addc_u32 s81, s81, 0
	s_add_i32 m0, s32, 0x8800
	s_nop 0
	global_load_lds_dwordx4 v130, s[80:81]
	s_add_i32 m0, m0, 0x2000
	s_cmp_eq_u32 s56, 4
	global_load_lds_dwordx4 v131, s[80:81]
	s_cbranch_scc0 .Lnod_a1
	s_mov_b32 m0, s5
	s_nop 0
	global_load_lds_dwordx4 v132, s[80:81]
	s_branch .Lnod_a1
.Ltl2_a1:
	s_nop 9
	s_branch .Lnod_a1
.Lrs_a1:
	v_max_f32_e32 v64, v176, v176
	v_max_f32_e32 v66, 0, v64
	v_exp_f32_e64 v176, -v66
	v_add_f32_e32 v173, v173, v66
	v_xor_b32_e32 v64, 0x80000000, v173
	v_pk_add_f32 v[96:97], v[96:97], v[66:67] op_sel_hi:[1,0] neg_lo:[0,1] neg_hi:[0,1]
	v_pk_add_f32 v[80:81], v[80:81], v[66:67] op_sel_hi:[1,0] neg_lo:[0,1] neg_hi:[0,1]
	v_pk_add_f32 v[98:99], v[98:99], v[66:67] op_sel_hi:[1,0] neg_lo:[0,1] neg_hi:[0,1]
	v_pk_add_f32 v[82:83], v[82:83], v[66:67] op_sel_hi:[1,0] neg_lo:[0,1] neg_hi:[0,1]
	v_pk_add_f32 v[100:101], v[100:101], v[66:67] op_sel_hi:[1,0] neg_lo:[0,1] neg_hi:[0,1]
	v_pk_add_f32 v[84:85], v[84:85], v[66:67] op_sel_hi:[1,0] neg_lo:[0,1] neg_hi:[0,1]
	v_pk_add_f32 v[102:103], v[102:103], v[66:67] op_sel_hi:[1,0] neg_lo:[0,1] neg_hi:[0,1]
	v_pk_add_f32 v[86:87], v[86:87], v[66:67] op_sel_hi:[1,0] neg_lo:[0,1] neg_hi:[0,1]
	v_pk_add_f32 v[104:105], v[104:105], v[66:67] op_sel_hi:[1,0] neg_lo:[0,1] neg_hi:[0,1]
	v_pk_add_f32 v[88:89], v[88:89], v[66:67] op_sel_hi:[1,0] neg_lo:[0,1] neg_hi:[0,1]
	v_pk_add_f32 v[106:107], v[106:107], v[66:67] op_sel_hi:[1,0] neg_lo:[0,1] neg_hi:[0,1]
	v_pk_add_f32 v[90:91], v[90:91], v[66:67] op_sel_hi:[1,0] neg_lo:[0,1] neg_hi:[0,1]
	v_pk_add_f32 v[108:109], v[108:109], v[66:67] op_sel_hi:[1,0] neg_lo:[0,1] neg_hi:[0,1]
	v_pk_add_f32 v[92:93], v[92:93], v[66:67] op_sel_hi:[1,0] neg_lo:[0,1] neg_hi:[0,1]
	v_pk_add_f32 v[110:111], v[110:111], v[66:67] op_sel_hi:[1,0] neg_lo:[0,1] neg_hi:[0,1]
	v_pk_add_f32 v[94:95], v[94:95], v[66:67] op_sel_hi:[1,0] neg_lo:[0,1] neg_hi:[0,1]
	v_mov_b32_e32 v65, v64
	v_mov_b32_e32 v66, v64
	v_mov_b32_e32 v67, v64
	v_mov_b32_e32 v68, v64
	v_mov_b32_e32 v69, v64
	v_mov_b32_e32 v70, v64
	v_mov_b32_e32 v71, v64
	v_mov_b32_e32 v72, v64
	v_mov_b32_e32 v73, v64
	v_mov_b32_e32 v74, v64
	v_mov_b32_e32 v75, v64
	v_mov_b32_e32 v76, v64
	v_mov_b32_e32 v77, v64
	v_mov_b32_e32 v78, v64
	v_mov_b32_e32 v79, v64
	v_pk_mul_f32 v[46:47], v[46:47], v[176:177] op_sel_hi:[1,0]
	v_pk_mul_f32 v[44:45], v[44:45], v[176:177] op_sel_hi:[1,0]
	v_pk_mul_f32 v[42:43], v[42:43], v[176:177] op_sel_hi:[1,0]
	v_pk_mul_f32 v[40:41], v[40:41], v[176:177] op_sel_hi:[1,0]
	v_pk_mul_f32 v[38:39], v[38:39], v[176:177] op_sel_hi:[1,0]
	v_pk_mul_f32 v[36:37], v[36:37], v[176:177] op_sel_hi:[1,0]
	v_pk_mul_f32 v[34:35], v[34:35], v[176:177] op_sel_hi:[1,0]
	v_pk_mul_f32 v[32:33], v[32:33], v[176:177] op_sel_hi:[1,0]
	v_pk_mul_f32 v[30:31], v[30:31], v[176:177] op_sel_hi:[1,0]
	v_pk_mul_f32 v[28:29], v[28:29], v[176:177] op_sel_hi:[1,0]
	v_pk_mul_f32 v[26:27], v[26:27], v[176:177] op_sel_hi:[1,0]
	v_pk_mul_f32 v[24:25], v[24:25], v[176:177] op_sel_hi:[1,0]
	v_pk_mul_f32 v[22:23], v[22:23], v[176:177] op_sel_hi:[1,0]
	v_pk_mul_f32 v[20:21], v[20:21], v[176:177] op_sel_hi:[1,0]
	v_pk_mul_f32 v[18:19], v[18:19], v[176:177] op_sel_hi:[1,0]
	v_pk_mul_f32 v[16:17], v[16:17], v[176:177] op_sel_hi:[1,0]
	v_pk_mul_f32 v[14:15], v[14:15], v[176:177] op_sel_hi:[1,0]
	v_pk_mul_f32 v[12:13], v[12:13], v[176:177] op_sel_hi:[1,0]
	v_pk_mul_f32 v[10:11], v[10:11], v[176:177] op_sel_hi:[1,0]
	v_pk_mul_f32 v[8:9], v[8:9], v[176:177] op_sel_hi:[1,0]
	v_pk_mul_f32 v[6:7], v[6:7], v[176:177] op_sel_hi:[1,0]
	v_pk_mul_f32 v[4:5], v[4:5], v[176:177] op_sel_hi:[1,0]
	v_pk_mul_f32 v[2:3], v[2:3], v[176:177] op_sel_hi:[1,0]
	v_pk_mul_f32 v[0:1], v[0:1], v[176:177] op_sel_hi:[1,0]
	v_pk_mul_f32 v[62:63], v[62:63], v[176:177] op_sel_hi:[1,0]
	v_pk_mul_f32 v[60:61], v[60:61], v[176:177] op_sel_hi:[1,0]
	v_pk_mul_f32 v[58:59], v[58:59], v[176:177] op_sel_hi:[1,0]
	v_pk_mul_f32 v[56:57], v[56:57], v[176:177] op_sel_hi:[1,0]
	v_pk_mul_f32 v[54:55], v[54:55], v[176:177] op_sel_hi:[1,0]
	v_pk_mul_f32 v[52:53], v[52:53], v[176:177] op_sel_hi:[1,0]
	v_pk_mul_f32 v[50:51], v[50:51], v[176:177] op_sel_hi:[1,0]
	v_pk_mul_f32 v[48:49], v[48:49], v[176:177] op_sel_hi:[1,0]
	v_mul_f32_e32 v172, v172, v176
	s_branch .Latt_a1_exp

.Ltl_a2:
	s_add_i32 s4, s65, 1
	s_cmp_ge_u32 s4, s66
	s_cbranch_scc1 .Ltl2_a2
	s_add_u32 s80, s80, 0x20000
	s_addc_u32 s81, s81, 0
	s_add_i32 m0, s32, 0xd800
	s_nop 0
	global_load_lds_dwordx4 v130, s[80:81]
	s_add_i32 m0, m0, 0x2000
	s_cmp_eq_u32 s56, 4
	global_load_lds_dwordx4 v131, s[80:81]
	s_cbranch_scc0 .Lnod_a2
	s_mov_b32 m0, s28
	s_nop 0
	global_load_lds_dwordx4 v132, s[80:81]
	s_branch .Lnod_a2
.Ltl2_a2:
	s_nop 9
	s_branch .Lnod_a2
.Lrs_a2:
	v_max_f32_e32 v64, v176, v176
	v_max_f32_e32 v66, 0, v64
	v_exp_f32_e64 v176, -v66
	v_add_f32_e32 v173, v173, v66
	v_xor_b32_e32 v64, 0x80000000, v173
	v_pk_add_f32 v[96:97], v[96:97], v[66:67] op_sel_hi:[1,0] neg_lo:[0,1] neg_hi:[0,1]
	v_pk_add_f32 v[80:81], v[80:81], v[66:67] op_sel_hi:[1,0] neg_lo:[0,1] neg_hi:[0,1]
	v_pk_add_f32 v[98:99], v[98:99], v[66:67] op_sel_hi:[1,0] neg_lo:[0,1] neg_hi:[0,1]
	v_pk_add_f32 v[82:83], v[82:83], v[66:67] op_sel_hi:[1,0] neg_lo:[0,1] neg_hi:[0,1]
	v_pk_add_f32 v[100:101], v[100:101], v[66:67] op_sel_hi:[1,0] neg_lo:[0,1] neg_hi:[0,1]
	v_pk_add_f32 v[84:85], v[84:85], v[66:67] op_sel_hi:[1,0] neg_lo:[0,1] neg_hi:[0,1]
	v_pk_add_f32 v[102:103], v[102:103], v[66:67] op_sel_hi:[1,0] neg_lo:[0,1] neg_hi:[0,1]
	v_pk_add_f32 v[86:87], v[86:87], v[66:67] op_sel_hi:[1,0] neg_lo:[0,1] neg_hi:[0,1]
	v_pk_add_f32 v[104:105], v[104:105], v[66:67] op_sel_hi:[1,0] neg_lo:[0,1] neg_hi:[0,1]
	v_pk_add_f32 v[88:89], v[88:89], v[66:67] op_sel_hi:[1,0] neg_lo:[0,1] neg_hi:[0,1]
	v_pk_add_f32 v[106:107], v[106:107], v[66:67] op_sel_hi:[1,0] neg_lo:[0,1] neg_hi:[0,1]
	v_pk_add_f32 v[90:91], v[90:91], v[66:67] op_sel_hi:[1,0] neg_lo:[0,1] neg_hi:[0,1]
	v_pk_add_f32 v[108:109], v[108:109], v[66:67] op_sel_hi:[1,0] neg_lo:[0,1] neg_hi:[0,1]
	v_pk_add_f32 v[92:93], v[92:93], v[66:67] op_sel_hi:[1,0] neg_lo:[0,1] neg_hi:[0,1]
	v_pk_add_f32 v[110:111], v[110:111], v[66:67] op_sel_hi:[1,0] neg_lo:[0,1] neg_hi:[0,1]
	v_pk_add_f32 v[94:95], v[94:95], v[66:67] op_sel_hi:[1,0] neg_lo:[0,1] neg_hi:[0,1]
	v_mov_b32_e32 v65, v64
	v_mov_b32_e32 v66, v64
	v_mov_b32_e32 v67, v64
	v_mov_b32_e32 v68, v64
	v_mov_b32_e32 v69, v64
	v_mov_b32_e32 v70, v64
	v_mov_b32_e32 v71, v64
	v_mov_b32_e32 v72, v64
	v_mov_b32_e32 v73, v64
	v_mov_b32_e32 v74, v64
	v_mov_b32_e32 v75, v64
	v_mov_b32_e32 v76, v64
	v_mov_b32_e32 v77, v64
	v_mov_b32_e32 v78, v64
	v_mov_b32_e32 v79, v64
	v_pk_mul_f32 v[46:47], v[46:47], v[176:177] op_sel_hi:[1,0]
	v_pk_mul_f32 v[44:45], v[44:45], v[176:177] op_sel_hi:[1,0]
	v_pk_mul_f32 v[42:43], v[42:43], v[176:177] op_sel_hi:[1,0]
	v_pk_mul_f32 v[40:41], v[40:41], v[176:177] op_sel_hi:[1,0]
	v_pk_mul_f32 v[38:39], v[38:39], v[176:177] op_sel_hi:[1,0]
	v_pk_mul_f32 v[36:37], v[36:37], v[176:177] op_sel_hi:[1,0]
	v_pk_mul_f32 v[34:35], v[34:35], v[176:177] op_sel_hi:[1,0]
	v_pk_mul_f32 v[32:33], v[32:33], v[176:177] op_sel_hi:[1,0]
	v_pk_mul_f32 v[30:31], v[30:31], v[176:177] op_sel_hi:[1,0]
	v_pk_mul_f32 v[28:29], v[28:29], v[176:177] op_sel_hi:[1,0]
	v_pk_mul_f32 v[26:27], v[26:27], v[176:177] op_sel_hi:[1,0]
	v_pk_mul_f32 v[24:25], v[24:25], v[176:177] op_sel_hi:[1,0]
	v_pk_mul_f32 v[22:23], v[22:23], v[176:177] op_sel_hi:[1,0]
	v_pk_mul_f32 v[20:21], v[20:21], v[176:177] op_sel_hi:[1,0]
	v_pk_mul_f32 v[18:19], v[18:19], v[176:177] op_sel_hi:[1,0]
	v_pk_mul_f32 v[16:17], v[16:17], v[176:177] op_sel_hi:[1,0]
	v_pk_mul_f32 v[14:15], v[14:15], v[176:177] op_sel_hi:[1,0]
	v_pk_mul_f32 v[12:13], v[12:13], v[176:177] op_sel_hi:[1,0]
	v_pk_mul_f32 v[10:11], v[10:11], v[176:177] op_sel_hi:[1,0]
	v_pk_mul_f32 v[8:9], v[8:9], v[176:177] op_sel_hi:[1,0]
	v_pk_mul_f32 v[6:7], v[6:7], v[176:177] op_sel_hi:[1,0]
	v_pk_mul_f32 v[4:5], v[4:5], v[176:177] op_sel_hi:[1,0]
	v_pk_mul_f32 v[2:3], v[2:3], v[176:177] op_sel_hi:[1,0]
	v_pk_mul_f32 v[0:1], v[0:1], v[176:177] op_sel_hi:[1,0]
	v_pk_mul_f32 v[62:63], v[62:63], v[176:177] op_sel_hi:[1,0]
	v_pk_mul_f32 v[60:61], v[60:61], v[176:177] op_sel_hi:[1,0]
	v_pk_mul_f32 v[58:59], v[58:59], v[176:177] op_sel_hi:[1,0]
	v_pk_mul_f32 v[56:57], v[56:57], v[176:177] op_sel_hi:[1,0]
	v_pk_mul_f32 v[54:55], v[54:55], v[176:177] op_sel_hi:[1,0]
	v_pk_mul_f32 v[52:53], v[52:53], v[176:177] op_sel_hi:[1,0]
	v_pk_mul_f32 v[50:51], v[50:51], v[176:177] op_sel_hi:[1,0]
	v_pk_mul_f32 v[48:49], v[48:49], v[176:177] op_sel_hi:[1,0]
	v_mul_f32_e32 v172, v172, v176
	s_branch .Latt_a2_exp

.Ltl_a0:
	s_add_i32 s4, s65, 1
	s_cmp_ge_u32 s4, s66
	s_cbranch_scc1 .Ltl2_a0
	s_add_u32 s80, s80, 0x20000
	s_addc_u32 s81, s81, 0
	s_add_i32 m0, s32, 0x12800
	s_nop 0
	global_load_lds_dwordx4 v130, s[80:81]
	s_add_i32 m0, m0, 0x2000
	s_cmp_eq_u32 s56, 4
	global_load_lds_dwordx4 v131, s[80:81]
	s_cbranch_scc0 .Lnod_a0
	s_mov_b32 m0, s29
	s_nop 0
	global_load_lds_dwordx4 v132, s[80:81]
	s_branch .Lnod_a0
.Ltl2_a0:
	s_nop 9
	s_branch .Lnod_a0
.Lrs_a0:
	v_max_f32_e32 v64, v176, v176
	v_max_f32_e32 v66, 0, v64
	v_exp_f32_e64 v176, -v66
	v_add_f32_e32 v173, v173, v66
	v_xor_b32_e32 v64, 0x80000000, v173
	v_pk_add_f32 v[96:97], v[96:97], v[66:67] op_sel_hi:[1,0] neg_lo:[0,1] neg_hi:[0,1]
	v_pk_add_f32 v[80:81], v[80:81], v[66:67] op_sel_hi:[1,0] neg_lo:[0,1] neg_hi:[0,1]
	v_pk_add_f32 v[98:99], v[98:99], v[66:67] op_sel_hi:[1,0] neg_lo:[0,1] neg_hi:[0,1]
	v_pk_add_f32 v[82:83], v[82:83], v[66:67] op_sel_hi:[1,0] neg_lo:[0,1] neg_hi:[0,1]
	v_pk_add_f32 v[100:101], v[100:101], v[66:67] op_sel_hi:[1,0] neg_lo:[0,1] neg_hi:[0,1]
	v_pk_add_f32 v[84:85], v[84:85], v[66:67] op_sel_hi:[1,0] neg_lo:[0,1] neg_hi:[0,1]
	v_pk_add_f32 v[102:103], v[102:103], v[66:67] op_sel_hi:[1,0] neg_lo:[0,1] neg_hi:[0,1]
	v_pk_add_f32 v[86:87], v[86:87], v[66:67] op_sel_hi:[1,0] neg_lo:[0,1] neg_hi:[0,1]
	v_pk_add_f32 v[104:105], v[104:105], v[66:67] op_sel_hi:[1,0] neg_lo:[0,1] neg_hi:[0,1]
	v_pk_add_f32 v[88:89], v[88:89], v[66:67] op_sel_hi:[1,0] neg_lo:[0,1] neg_hi:[0,1]
	v_pk_add_f32 v[106:107], v[106:107], v[66:67] op_sel_hi:[1,0] neg_lo:[0,1] neg_hi:[0,1]
	v_pk_add_f32 v[90:91], v[90:91], v[66:67] op_sel_hi:[1,0] neg_lo:[0,1] neg_hi:[0,1]
	v_pk_add_f32 v[108:109], v[108:109], v[66:67] op_sel_hi:[1,0] neg_lo:[0,1] neg_hi:[0,1]
	v_pk_add_f32 v[92:93], v[92:93], v[66:67] op_sel_hi:[1,0] neg_lo:[0,1] neg_hi:[0,1]
	v_pk_add_f32 v[110:111], v[110:111], v[66:67] op_sel_hi:[1,0] neg_lo:[0,1] neg_hi:[0,1]
	v_pk_add_f32 v[94:95], v[94:95], v[66:67] op_sel_hi:[1,0] neg_lo:[0,1] neg_hi:[0,1]
	v_mov_b32_e32 v65, v64
	v_mov_b32_e32 v66, v64
	v_mov_b32_e32 v67, v64
	v_mov_b32_e32 v68, v64
	v_mov_b32_e32 v69, v64
	v_mov_b32_e32 v70, v64
	v_mov_b32_e32 v71, v64
	v_mov_b32_e32 v72, v64
	v_mov_b32_e32 v73, v64
	v_mov_b32_e32 v74, v64
	v_mov_b32_e32 v75, v64
	v_mov_b32_e32 v76, v64
	v_mov_b32_e32 v77, v64
	v_mov_b32_e32 v78, v64
	v_mov_b32_e32 v79, v64
	v_pk_mul_f32 v[46:47], v[46:47], v[176:177] op_sel_hi:[1,0]
	v_pk_mul_f32 v[44:45], v[44:45], v[176:177] op_sel_hi:[1,0]
	v_pk_mul_f32 v[42:43], v[42:43], v[176:177] op_sel_hi:[1,0]
	v_pk_mul_f32 v[40:41], v[40:41], v[176:177] op_sel_hi:[1,0]
	v_pk_mul_f32 v[38:39], v[38:39], v[176:177] op_sel_hi:[1,0]
	v_pk_mul_f32 v[36:37], v[36:37], v[176:177] op_sel_hi:[1,0]
	v_pk_mul_f32 v[34:35], v[34:35], v[176:177] op_sel_hi:[1,0]
	v_pk_mul_f32 v[32:33], v[32:33], v[176:177] op_sel_hi:[1,0]
	v_pk_mul_f32 v[30:31], v[30:31], v[176:177] op_sel_hi:[1,0]
	v_pk_mul_f32 v[28:29], v[28:29], v[176:177] op_sel_hi:[1,0]
	v_pk_mul_f32 v[26:27], v[26:27], v[176:177] op_sel_hi:[1,0]
	v_pk_mul_f32 v[24:25], v[24:25], v[176:177] op_sel_hi:[1,0]
	v_pk_mul_f32 v[22:23], v[22:23], v[176:177] op_sel_hi:[1,0]
	v_pk_mul_f32 v[20:21], v[20:21], v[176:177] op_sel_hi:[1,0]
	v_pk_mul_f32 v[18:19], v[18:19], v[176:177] op_sel_hi:[1,0]
	v_pk_mul_f32 v[16:17], v[16:17], v[176:177] op_sel_hi:[1,0]
	v_pk_mul_f32 v[14:15], v[14:15], v[176:177] op_sel_hi:[1,0]
	v_pk_mul_f32 v[12:13], v[12:13], v[176:177] op_sel_hi:[1,0]
	v_pk_mul_f32 v[10:11], v[10:11], v[176:177] op_sel_hi:[1,0]
	v_pk_mul_f32 v[8:9], v[8:9], v[176:177] op_sel_hi:[1,0]
	v_pk_mul_f32 v[6:7], v[6:7], v[176:177] op_sel_hi:[1,0]
	v_pk_mul_f32 v[4:5], v[4:5], v[176:177] op_sel_hi:[1,0]
	v_pk_mul_f32 v[2:3], v[2:3], v[176:177] op_sel_hi:[1,0]
	v_pk_mul_f32 v[0:1], v[0:1], v[176:177] op_sel_hi:[1,0]
	v_pk_mul_f32 v[62:63], v[62:63], v[176:177] op_sel_hi:[1,0]
	v_pk_mul_f32 v[60:61], v[60:61], v[176:177] op_sel_hi:[1,0]
	v_pk_mul_f32 v[58:59], v[58:59], v[176:177] op_sel_hi:[1,0]
	v_pk_mul_f32 v[56:57], v[56:57], v[176:177] op_sel_hi:[1,0]
	v_pk_mul_f32 v[54:55], v[54:55], v[176:177] op_sel_hi:[1,0]
	v_pk_mul_f32 v[52:53], v[52:53], v[176:177] op_sel_hi:[1,0]
	v_pk_mul_f32 v[50:51], v[50:51], v[176:177] op_sel_hi:[1,0]
	v_pk_mul_f32 v[48:49], v[48:49], v[176:177] op_sel_hi:[1,0]
	v_mul_f32_e32 v172, v172, v176
	s_branch .Latt_a0_exp
